# final RMSNorm pass: sum-of-squares loads run two row groups ahead into spare registers; stores never drained by counted waits
# baseline (speedup 1.0000x reference)
;     __device__ __forceinline__ void after(f32x4 (&acc)[2][2][4][2], const Unit& u, int wr, int wc, int fr, int fq) const {
;     ...
;         f32x4 gn[2][2];
; #pragma unroll
;         for (int bj = 0; bj < 2; ++bj)
; #pragma unroll
;             for (int n = 0; n < 2; ++n) gn[bj][n] = *(const f32x4*)(gain + 256 * u.pn + 64 * wc + 32 * bj + 8 * fq + 4 * n);
; #pragma unroll
;         for (int ai = 0; ai < 2; ++ai)
; #pragma unroll
;             for (int m = 0; m < 4; ++m) {
;                 const int row = 256 * u.pm + 128 * ai + 64 * wr + 16 * m + fr;
;                 const f32x4* sp = (const f32x4*)(SSQ + row * 16);
;                 const f32x4 s0 = sp[0], s1 = sp[1], s2 = sp[2], s3 = sp[3];
;                 const float tot = ((s0[0] + s0[1]) + (s0[2] + s0[3])) + ((s1[0] + s1[1]) + (s1[2] + s1[3])) + ((s2[0] + s2[1]) + (s2[2] + s2[3])) + ((s3[0] + s3[1]) + (s3[2] + s3[3]));
;                 const float rinv = 1.0f / sqrtf(tot * (1.f / DM) + 1e-6f);
; #pragma unroll
;                 for (int bj = 0; bj < 2; ++bj)
; #pragma unroll
;                     for (int n = 0; n < 2; ++n) {
;                         const int col = 256 * u.pn + 64 * wc + 32 * bj + 8 * fq + 4 * n;
;                         *(f32x4*)(out + (size_t)row * 1024 + col) = acc[ai][bj][m][n] * rinv * gn[bj][n];
.LBB0_567:
	s_or_b64 exec, exec, s[2:3]
	s_lshl_b32 s0, s10, 8
	s_ashr_i32 s1, s0, 31
	s_lshl_b64 s[2:3], s[0:1], 2
	s_add_u32 s1, s72, s2
	s_addc_u32 s3, s73, s3
	s_lshl_b32 s2, s11, 2
	s_add_u32 s2, s1, s2
	s_addc_u32 s3, s3, 0
	s_lshl_b32 s1, s8, 8
	s_add_i32 s1, s1, s9
	v_or_b32_e32 v146, s1, v195
	s_waitcnt lgkmcnt(0)
	v_lshlrev_b32_e32 v128, 4, v146
	v_ashrrev_i32_e32 v129, 31, v128
	v_lshl_add_u64 v[128:129], v[128:129], 2, s[6:7]
	v_mov_b64_e32 v[244:245], v[128:129]
	s_mov_b32 s98, 0x2000
	s_mov_b32 s99, 0
	v_lshl_add_u64 v[246:247], v[244:245], 0, s[98:99]
	s_barrier
	global_load_dwordx4 v[150:153], v[128:129], off
	global_load_dwordx4 v[154:157], v[128:129], off offset:16
	global_load_dwordx4 v[158:161], v[128:129], off offset:32
	global_load_dwordx4 v[162:165], v[128:129], off offset:48
	v_lshlrev_b32_e32 v128, 2, v194
	global_load_dwordx4 v[140:143], v128, s[2:3]
	global_load_dwordx4 v[136:139], v128, s[2:3] offset:16
	global_load_dwordx4 v[132:135], v128, s[2:3] offset:128
	s_nop 0
	global_load_dwordx4 v[128:131], v128, s[2:3] offset:144
	global_load_dwordx4 v[228:231], v[244:245], off offset:1024
	global_load_dwordx4 v[232:235], v[244:245], off offset:1040
	global_load_dwordx4 v[236:239], v[244:245], off offset:1056
	global_load_dwordx4 v[240:243], v[244:245], off offset:1072
	global_load_dwordx4 v[176:179], v[244:245], off offset:2048
	global_load_dwordx4 v[180:183], v[244:245], off offset:2064
	global_load_dwordx4 v[184:187], v[244:245], off offset:2080
	global_load_dwordx4 v[188:191], v[244:245], off offset:2096
	v_ashrrev_i32_e32 v147, 31, v146
	v_mov_b32_e32 v149, 0x358637bd
	v_lshlrev_b64 v[168:169], 12, v[146:147]
	s_mov_b32 s2, 0xf800000
	v_or_b32_e32 v144, s11, v194
	v_or_b32_e32 v144, s0, v144
	v_mov_b32_e32 v148, 0x260
	v_ashrrev_i32_e32 v145, 31, v144
	v_or_b32_e32 v166, 16, v146
	v_lshlrev_b64 v[144:145], 2, v[144:145]
	v_lshlrev_b32_e32 v170, 4, v166
	v_ashrrev_i32_e32 v171, 31, v170
	v_ashrrev_i32_e32 v167, 31, v166
	s_waitcnt vmcnt(15)
	v_mov_b32_e32 v172, v151
	v_mov_b32_e32 v173, v152
	v_mov_b32_e32 v151, v153
	s_waitcnt vmcnt(14)
	v_mov_b32_e32 v152, v155
	v_mov_b32_e32 v153, v156
	v_mov_b32_e32 v155, v157
	v_pk_add_f32 v[150:151], v[172:173], v[150:151]
	v_pk_add_f32 v[152:153], v[152:153], v[154:155]
	v_pk_add_f32 v[150:151], v[150:151], v[150:151] op_sel:[0,1] op_sel_hi:[1,0]
	v_pk_add_f32 v[152:153], v[152:153], v[152:153] op_sel:[0,1] op_sel_hi:[1,0]
	s_waitcnt vmcnt(13)
	v_add_f32_e32 v156, v158, v159
	v_add_f32_e32 v158, v160, v161
	s_waitcnt vmcnt(12)
	v_mov_b32_e32 v157, v164
	v_mov_b32_e32 v159, v165
	v_mov_b32_e32 v151, v162
	v_mov_b32_e32 v153, v163
	v_pk_add_f32 v[154:155], v[156:157], v[158:159]
	v_pk_add_f32 v[150:151], v[150:151], v[152:153]
	s_nop 0
	v_pk_add_f32 v[150:151], v[150:151], v[154:155]
	s_nop 0
	v_add_f32_e32 v147, v150, v151
	v_fmamk_f32 v147, v147, 0x3a800000, v149
	v_mul_f32_e32 v150, 0x4f800000, v147
	v_cmp_gt_f32_e32 vcc, s2, v147
	s_nop 1
	v_cndmask_b32_e32 v147, v147, v150, vcc
	v_sqrt_f32_e32 v152, v147
	v_lshl_add_u64 v[150:151], s[74:75], 0, v[168:169]
	v_lshl_add_u64 v[150:151], v[150:151], 0, v[144:145]
	v_add_u32_e32 v153, -1, v152
	v_add_u32_e32 v154, 1, v152
	v_fma_f32 v155, -v153, v152, v147
	v_fma_f32 v156, -v154, v152, v147
	v_cmp_ge_f32_e64 s[0:1], 0, v155
	s_nop 1
	v_cndmask_b32_e64 v152, v152, v153, s[0:1]
	v_cmp_lt_f32_e64 s[0:1], 0, v156
	s_nop 1
	v_cndmask_b32_e64 v152, v152, v154, s[0:1]
	v_mul_f32_e32 v153, 0x37800000, v152
	v_cndmask_b32_e32 v152, v152, v153, vcc
	v_cmp_class_f32_e32 vcc, v147, v148
	s_nop 1
	v_cndmask_b32_e32 v147, v152, v147, vcc
	v_div_scale_f32 v154, s[0:1], v147, v147, 1.0
	v_rcp_f32_e32 v155, v154
	v_div_scale_f32 v156, vcc, 1.0, v147, 1.0
	v_lshl_add_u64 v[152:153], v[170:171], 2, s[6:7]
	v_fma_f32 v157, -v154, v155, 1.0
	v_fmac_f32_e32 v155, v157, v155
	v_mul_f32_e32 v157, v156, v155
	v_fma_f32 v158, -v154, v157, v156
	v_fmac_f32_e32 v157, v158, v155
	v_fma_f32 v154, -v154, v157, v156
	v_div_fmas_f32 v154, v154, v155, v157
	v_div_fixup_f32 v154, v154, v147, 1.0
	v_pk_mul_f32 v[124:125], v[124:125], v[154:155] op_sel_hi:[1,0]
	v_pk_mul_f32 v[126:127], v[126:127], v[154:155] op_sel_hi:[1,0]
	v_pk_mul_f32 v[120:121], v[120:121], v[154:155] op_sel_hi:[1,0]
	v_pk_mul_f32 v[122:123], v[122:123], v[154:155] op_sel_hi:[1,0]
	v_pk_mul_f32 v[156:157], v[116:117], v[154:155] op_sel_hi:[1,0]
	v_pk_mul_f32 v[158:159], v[118:119], v[154:155] op_sel_hi:[1,0]
	v_pk_mul_f32 v[160:161], v[112:113], v[154:155] op_sel_hi:[1,0]
	v_pk_mul_f32 v[154:155], v[114:115], v[154:155] op_sel_hi:[1,0]
	s_waitcnt vmcnt(11)
	v_pk_mul_f32 v[198:199], v[142:143], v[126:127]
	v_pk_mul_f32 v[196:197], v[140:141], v[124:125]
	s_waitcnt vmcnt(10)
	v_pk_mul_f32 v[202:203], v[138:139], v[122:123]
	v_pk_mul_f32 v[200:201], v[136:137], v[120:121]
	s_waitcnt vmcnt(9)
	v_pk_mul_f32 v[206:207], v[134:135], v[158:159]
	v_pk_mul_f32 v[204:205], v[132:133], v[156:157]
	s_waitcnt vmcnt(8)
	v_pk_mul_f32 v[210:211], v[130:131], v[154:155]
	v_pk_mul_f32 v[208:209], v[128:129], v[160:161]
	s_waitcnt vmcnt(4)
;     __device__ __forceinline__ void after(f32x4 (&acc)[2][2][4][2], const Unit& u, int wr, int wc, int fr, int fq) const {
;     ...
; #pragma unroll
;         for (int ai = 0; ai < 2; ++ai)
; #pragma unroll
;             for (int m = 0; m < 4; ++m) {
;                 const int row = 256 * u.pm + 128 * ai + 64 * wr + 16 * m + fr;
;                 const f32x4* sp = (const f32x4*)(SSQ + row * 16);
;                 const f32x4 s0 = sp[0], s1 = sp[1], s2 = sp[2], s3 = sp[3];
;                 const float tot = ((s0[0] + s0[1]) + (s0[2] + s0[3])) + ((s1[0] + s1[1]) + (s1[2] + s1[3])) + ((s2[0] + s2[1]) + (s2[2] + s2[3])) + ((s3[0] + s3[1]) + (s3[2] + s3[3]));
;                 const float rinv = 1.0f / sqrtf(tot * (1.f / DM) + 1e-6f);
; #pragma unroll
;                 for (int bj = 0; bj < 2; ++bj)
; #pragma unroll
;                     for (int n = 0; n < 2; ++n) {
;                         const int col = 256 * u.pn + 64 * wc + 32 * bj + 8 * fq + 4 * n;
;                         *(f32x4*)(out + (size_t)row * 1024 + col) = acc[ai][bj][m][n] * rinv * gn[bj][n];
;                     }
;             }
	v_mov_b32_e32 v112, v228
	v_mov_b32_e32 v113, v229
	v_mov_b32_e32 v114, v230
	v_mov_b32_e32 v115, v231
	v_mov_b32_e32 v116, v232
	v_mov_b32_e32 v117, v233
	v_mov_b32_e32 v118, v234
	v_mov_b32_e32 v119, v235
	v_mov_b32_e32 v120, v236
	v_mov_b32_e32 v121, v237
	v_mov_b32_e32 v122, v238
	v_mov_b32_e32 v123, v239
	v_mov_b32_e32 v124, v240
	v_mov_b32_e32 v125, v241
	v_mov_b32_e32 v126, v242
	v_mov_b32_e32 v127, v243
	global_load_dwordx4 v[228:231], v[244:245], off offset:3072
	global_load_dwordx4 v[232:235], v[244:245], off offset:3088
	global_load_dwordx4 v[236:239], v[244:245], off offset:3104
	global_load_dwordx4 v[240:243], v[244:245], off offset:3120
	global_store_dwordx4 v[150:151], v[196:199], off
	global_store_dwordx4 v[150:151], v[200:203], off offset:16
	global_store_dwordx4 v[150:151], v[204:207], off offset:128
	global_store_dwordx4 v[150:151], v[208:211], off offset:144
	v_or_b32_e32 v150, 32, v146
	v_lshlrev_b64 v[154:155], 12, v[166:167]
	v_lshlrev_b32_e32 v152, 4, v150
	v_ashrrev_i32_e32 v153, 31, v152
	v_ashrrev_i32_e32 v151, 31, v150
	v_mov_b32_e32 v156, v113
	v_mov_b32_e32 v157, v114
	v_mov_b32_e32 v113, v115
	v_mov_b32_e32 v114, v117
	v_mov_b32_e32 v115, v118
	v_mov_b32_e32 v117, v119
	v_pk_add_f32 v[112:113], v[156:157], v[112:113]
	v_pk_add_f32 v[114:115], v[114:115], v[116:117]
	v_pk_add_f32 v[112:113], v[112:113], v[112:113] op_sel:[0,1] op_sel_hi:[1,0]
	v_pk_add_f32 v[114:115], v[114:115], v[114:115] op_sel:[0,1] op_sel_hi:[1,0]
	v_add_f32_e32 v118, v120, v121
	v_add_f32_e32 v120, v122, v123
	v_mov_b32_e32 v119, v126
	v_mov_b32_e32 v121, v127
	v_mov_b32_e32 v113, v124
	v_mov_b32_e32 v115, v125
	v_pk_add_f32 v[116:117], v[118:119], v[120:121]
	v_pk_add_f32 v[112:113], v[112:113], v[114:115]
	v_lshl_add_u64 v[114:115], v[152:153], 2, s[6:7]
	v_pk_add_f32 v[112:113], v[112:113], v[116:117]
	s_nop 0
	v_add_f32_e32 v112, v112, v113
	v_fmamk_f32 v112, v112, 0x3a800000, v149
	v_mul_f32_e32 v113, 0x4f800000, v112
	v_cmp_gt_f32_e32 vcc, s2, v112
	s_nop 1
	v_cndmask_b32_e32 v116, v112, v113, vcc
	v_sqrt_f32_e32 v117, v116
	v_lshl_add_u64 v[112:113], s[74:75], 0, v[154:155]
	v_lshl_add_u64 v[112:113], v[112:113], 0, v[144:145]
	v_add_u32_e32 v118, -1, v117
	v_add_u32_e32 v119, 1, v117
	v_fma_f32 v120, -v118, v117, v116
	v_fma_f32 v121, -v119, v117, v116
	v_cmp_ge_f32_e64 s[0:1], 0, v120
	s_nop 1
	v_cndmask_b32_e64 v117, v117, v118, s[0:1]
	v_cmp_lt_f32_e64 s[0:1], 0, v121
	s_nop 1
	v_cndmask_b32_e64 v117, v117, v119, s[0:1]
	v_mul_f32_e32 v118, 0x37800000, v117
	v_cndmask_b32_e32 v117, v117, v118, vcc
	v_cmp_class_f32_e32 vcc, v116, v148
	s_nop 1
	v_cndmask_b32_e32 v116, v117, v116, vcc
	v_div_scale_f32 v117, s[0:1], v116, v116, 1.0
	v_rcp_f32_e32 v118, v117
	v_div_scale_f32 v119, vcc, 1.0, v116, 1.0
	v_fma_f32 v120, -v117, v118, 1.0
	v_fmac_f32_e32 v118, v120, v118
	v_mul_f32_e32 v120, v119, v118
	v_fma_f32 v121, -v117, v120, v119
	v_fmac_f32_e32 v120, v121, v118
	v_fma_f32 v117, -v117, v120, v119
	v_div_fmas_f32 v117, v117, v118, v120
	v_div_fixup_f32 v116, v117, v116, 1.0
	v_pk_mul_f32 v[108:109], v[108:109], v[116:117] op_sel_hi:[1,0]
	v_pk_mul_f32 v[110:111], v[110:111], v[116:117] op_sel_hi:[1,0]
	v_pk_mul_f32 v[104:105], v[104:105], v[116:117] op_sel_hi:[1,0]
	v_pk_mul_f32 v[106:107], v[106:107], v[116:117] op_sel_hi:[1,0]
	v_pk_mul_f32 v[118:119], v[100:101], v[116:117] op_sel_hi:[1,0]
	v_pk_mul_f32 v[120:121], v[102:103], v[116:117] op_sel_hi:[1,0]
	v_pk_mul_f32 v[122:123], v[96:97], v[116:117] op_sel_hi:[1,0]
	v_pk_mul_f32 v[116:117], v[98:99], v[116:117] op_sel_hi:[1,0]
	v_pk_mul_f32 v[214:215], v[142:143], v[110:111]
	v_pk_mul_f32 v[212:213], v[140:141], v[108:109]
	v_pk_mul_f32 v[218:219], v[138:139], v[106:107]
	v_pk_mul_f32 v[216:217], v[136:137], v[104:105]
	v_pk_mul_f32 v[222:223], v[134:135], v[120:121]
	v_pk_mul_f32 v[220:221], v[132:133], v[118:119]
	v_pk_mul_f32 v[226:227], v[130:131], v[116:117]
	v_pk_mul_f32 v[224:225], v[128:129], v[122:123]
	s_waitcnt vmcnt(8)
	v_mov_b32_e32 v96, v176
	v_mov_b32_e32 v97, v177
	v_mov_b32_e32 v98, v178
	v_mov_b32_e32 v99, v179
	v_mov_b32_e32 v100, v180
	v_mov_b32_e32 v101, v181
	v_mov_b32_e32 v102, v182
	v_mov_b32_e32 v103, v183
	v_mov_b32_e32 v104, v184
	v_mov_b32_e32 v105, v185
	v_mov_b32_e32 v106, v186
	v_mov_b32_e32 v107, v187
	v_mov_b32_e32 v108, v188
	v_mov_b32_e32 v109, v189
	v_mov_b32_e32 v110, v190
	v_mov_b32_e32 v111, v191
	global_load_dwordx4 v[176:179], v[246:247], off
	global_load_dwordx4 v[180:183], v[246:247], off offset:16
	global_load_dwordx4 v[184:187], v[246:247], off offset:32
	global_load_dwordx4 v[188:191], v[246:247], off offset:48
	global_store_dwordx4 v[112:113], v[212:215], off
	global_store_dwordx4 v[112:113], v[216:219], off offset:16
	global_store_dwordx4 v[112:113], v[220:223], off offset:128
	global_store_dwordx4 v[112:113], v[224:227], off offset:144
	v_or_b32_e32 v112, 48, v146
	v_lshlrev_b64 v[116:117], 12, v[150:151]
	v_lshlrev_b32_e32 v114, 4, v112
	v_ashrrev_i32_e32 v115, 31, v114
	v_ashrrev_i32_e32 v113, 31, v112
	v_mov_b32_e32 v118, v97
	v_mov_b32_e32 v119, v98
	v_mov_b32_e32 v97, v99
	v_mov_b32_e32 v98, v101
	v_mov_b32_e32 v99, v102
	v_mov_b32_e32 v101, v103
	v_pk_add_f32 v[96:97], v[118:119], v[96:97]
	v_pk_add_f32 v[98:99], v[98:99], v[100:101]
	v_pk_add_f32 v[96:97], v[96:97], v[96:97] op_sel:[0,1] op_sel_hi:[1,0]
	v_pk_add_f32 v[98:99], v[98:99], v[98:99] op_sel:[0,1] op_sel_hi:[1,0]
	v_add_f32_e32 v102, v104, v105
	v_add_f32_e32 v104, v106, v107
	v_mov_b32_e32 v103, v110
	v_mov_b32_e32 v105, v111
	v_mov_b32_e32 v97, v108
	v_mov_b32_e32 v99, v109
	v_pk_add_f32 v[100:101], v[102:103], v[104:105]
	v_pk_add_f32 v[96:97], v[96:97], v[98:99]
;     __device__ __forceinline__ void after(f32x4 (&acc)[2][2][4][2], const Unit& u, int wr, int wc, int fr, int fq) const {
;     ...
; #pragma unroll
;         for (int ai = 0; ai < 2; ++ai)
; #pragma unroll
;             for (int m = 0; m < 4; ++m) {
;                 const int row = 256 * u.pm + 128 * ai + 64 * wr + 16 * m + fr;
;                 const f32x4* sp = (const f32x4*)(SSQ + row * 16);
;                 const f32x4 s0 = sp[0], s1 = sp[1], s2 = sp[2], s3 = sp[3];
;                 const float tot = ((s0[0] + s0[1]) + (s0[2] + s0[3])) + ((s1[0] + s1[1]) + (s1[2] + s1[3])) + ((s2[0] + s2[1]) + (s2[2] + s2[3])) + ((s3[0] + s3[1]) + (s3[2] + s3[3]));
;                 const float rinv = 1.0f / sqrtf(tot * (1.f / DM) + 1e-6f);
; #pragma unroll
;                 for (int bj = 0; bj < 2; ++bj)
; #pragma unroll
;                     for (int n = 0; n < 2; ++n) {
;                         const int col = 256 * u.pn + 64 * wc + 32 * bj + 8 * fq + 4 * n;
;                         *(f32x4*)(out + (size_t)row * 1024 + col) = acc[ai][bj][m][n] * rinv * gn[bj][n];
;                     }
;             }
	v_lshl_add_u64 v[98:99], v[114:115], 2, s[6:7]
	v_pk_add_f32 v[96:97], v[96:97], v[100:101]
	s_nop 0
	v_add_f32_e32 v96, v96, v97
	v_fmamk_f32 v96, v96, 0x3a800000, v149
	v_mul_f32_e32 v97, 0x4f800000, v96
	v_cmp_gt_f32_e32 vcc, s2, v96
	s_nop 1
	v_cndmask_b32_e32 v100, v96, v97, vcc
	v_sqrt_f32_e32 v101, v100
	v_lshl_add_u64 v[96:97], s[74:75], 0, v[116:117]
	v_lshl_add_u64 v[96:97], v[96:97], 0, v[144:145]
	v_add_u32_e32 v102, -1, v101
	v_add_u32_e32 v103, 1, v101
	v_fma_f32 v104, -v102, v101, v100
	v_fma_f32 v105, -v103, v101, v100
	v_cmp_ge_f32_e64 s[0:1], 0, v104
	s_nop 1
	v_cndmask_b32_e64 v101, v101, v102, s[0:1]
	v_cmp_lt_f32_e64 s[0:1], 0, v105
	s_nop 1
	v_cndmask_b32_e64 v101, v101, v103, s[0:1]
	v_mul_f32_e32 v102, 0x37800000, v101
	v_cndmask_b32_e32 v101, v101, v102, vcc
	v_cmp_class_f32_e32 vcc, v100, v148
	s_nop 1
	v_cndmask_b32_e32 v100, v101, v100, vcc
	v_div_scale_f32 v101, s[0:1], v100, v100, 1.0
	v_rcp_f32_e32 v102, v101
	v_div_scale_f32 v103, vcc, 1.0, v100, 1.0
	v_fma_f32 v104, -v101, v102, 1.0
	v_fmac_f32_e32 v102, v104, v102
	v_mul_f32_e32 v104, v103, v102
	v_fma_f32 v105, -v101, v104, v103
	v_fmac_f32_e32 v104, v105, v102
	v_fma_f32 v101, -v101, v104, v103
	v_div_fmas_f32 v101, v101, v102, v104
	v_div_fixup_f32 v100, v101, v100, 1.0
	v_pk_mul_f32 v[92:93], v[92:93], v[100:101] op_sel_hi:[1,0]
	v_pk_mul_f32 v[94:95], v[94:95], v[100:101] op_sel_hi:[1,0]
	v_pk_mul_f32 v[88:89], v[88:89], v[100:101] op_sel_hi:[1,0]
	v_pk_mul_f32 v[90:91], v[90:91], v[100:101] op_sel_hi:[1,0]
	v_pk_mul_f32 v[102:103], v[84:85], v[100:101] op_sel_hi:[1,0]
	v_pk_mul_f32 v[104:105], v[86:87], v[100:101] op_sel_hi:[1,0]
	v_pk_mul_f32 v[106:107], v[80:81], v[100:101] op_sel_hi:[1,0]
	v_pk_mul_f32 v[100:101], v[82:83], v[100:101] op_sel_hi:[1,0]
	v_pk_mul_f32 v[198:199], v[142:143], v[94:95]
	v_pk_mul_f32 v[196:197], v[140:141], v[92:93]
	v_pk_mul_f32 v[202:203], v[138:139], v[90:91]
	v_pk_mul_f32 v[200:201], v[136:137], v[88:89]
	v_pk_mul_f32 v[206:207], v[134:135], v[104:105]
	v_pk_mul_f32 v[204:205], v[132:133], v[102:103]
	v_pk_mul_f32 v[210:211], v[130:131], v[100:101]
	v_pk_mul_f32 v[208:209], v[128:129], v[106:107]
	s_waitcnt vmcnt(12)
	v_mov_b32_e32 v80, v228
	v_mov_b32_e32 v81, v229
	v_mov_b32_e32 v82, v230
	v_mov_b32_e32 v83, v231
	v_mov_b32_e32 v84, v232
	v_mov_b32_e32 v85, v233
	v_mov_b32_e32 v86, v234
	v_mov_b32_e32 v87, v235
	v_mov_b32_e32 v88, v236
	v_mov_b32_e32 v89, v237
	v_mov_b32_e32 v90, v238
	v_mov_b32_e32 v91, v239
	v_mov_b32_e32 v92, v240
	v_mov_b32_e32 v93, v241
	v_mov_b32_e32 v94, v242
	v_mov_b32_e32 v95, v243
	global_load_dwordx4 v[228:231], v[246:247], off offset:1024
	global_load_dwordx4 v[232:235], v[246:247], off offset:1040
	global_load_dwordx4 v[236:239], v[246:247], off offset:1056
	global_load_dwordx4 v[240:243], v[246:247], off offset:1072
	global_store_dwordx4 v[96:97], v[196:199], off
	global_store_dwordx4 v[96:97], v[200:203], off offset:16
	global_store_dwordx4 v[96:97], v[204:207], off offset:128
	global_store_dwordx4 v[96:97], v[208:211], off offset:144
	v_add_u32_e32 v96, 0x80, v146
	v_lshlrev_b64 v[100:101], 12, v[112:113]
	v_lshlrev_b32_e32 v98, 4, v96
	v_ashrrev_i32_e32 v99, 31, v98
	v_ashrrev_i32_e32 v97, 31, v96
	v_mov_b32_e32 v102, v81
	v_mov_b32_e32 v103, v82
	v_mov_b32_e32 v81, v83
	v_mov_b32_e32 v82, v85
	v_mov_b32_e32 v83, v86
	v_mov_b32_e32 v85, v87
	v_pk_add_f32 v[80:81], v[102:103], v[80:81]
	v_pk_add_f32 v[82:83], v[82:83], v[84:85]
	v_pk_add_f32 v[80:81], v[80:81], v[80:81] op_sel:[0,1] op_sel_hi:[1,0]
	v_pk_add_f32 v[82:83], v[82:83], v[82:83] op_sel:[0,1] op_sel_hi:[1,0]
	v_add_f32_e32 v86, v88, v89
	v_add_f32_e32 v88, v90, v91
	v_mov_b32_e32 v87, v94
	v_mov_b32_e32 v89, v95
	v_mov_b32_e32 v81, v92
	v_mov_b32_e32 v83, v93
	v_pk_add_f32 v[84:85], v[86:87], v[88:89]
	v_pk_add_f32 v[80:81], v[80:81], v[82:83]
	v_lshl_add_u64 v[82:83], v[98:99], 2, s[6:7]
	v_pk_add_f32 v[80:81], v[80:81], v[84:85]
	s_nop 0
	v_add_f32_e32 v80, v80, v81
	v_fmamk_f32 v80, v80, 0x3a800000, v149
	v_mul_f32_e32 v81, 0x4f800000, v80
	v_cmp_gt_f32_e32 vcc, s2, v80
	s_nop 1
	v_cndmask_b32_e32 v84, v80, v81, vcc
	v_sqrt_f32_e32 v85, v84
	v_lshl_add_u64 v[80:81], s[74:75], 0, v[100:101]
	v_lshl_add_u64 v[80:81], v[80:81], 0, v[144:145]
	v_add_u32_e32 v86, -1, v85
	v_add_u32_e32 v87, 1, v85
	v_fma_f32 v88, -v86, v85, v84
	v_fma_f32 v89, -v87, v85, v84
	v_cmp_ge_f32_e64 s[0:1], 0, v88
	s_nop 1
	v_cndmask_b32_e64 v85, v85, v86, s[0:1]
	v_cmp_lt_f32_e64 s[0:1], 0, v89
	s_nop 1
	v_cndmask_b32_e64 v85, v85, v87, s[0:1]
	v_mul_f32_e32 v86, 0x37800000, v85
	v_cndmask_b32_e32 v85, v85, v86, vcc
	v_cmp_class_f32_e32 vcc, v84, v148
	s_nop 1
	v_cndmask_b32_e32 v84, v85, v84, vcc
	v_div_scale_f32 v85, s[0:1], v84, v84, 1.0
	v_rcp_f32_e32 v86, v85
	v_div_scale_f32 v87, vcc, 1.0, v84, 1.0
	v_fma_f32 v88, -v85, v86, 1.0
	v_fmac_f32_e32 v86, v88, v86
	v_mul_f32_e32 v88, v87, v86
	v_fma_f32 v89, -v85, v88, v87
	v_fmac_f32_e32 v88, v89, v86
	v_fma_f32 v85, -v85, v88, v87
	v_div_fmas_f32 v85, v85, v86, v88
	v_div_fixup_f32 v84, v85, v84, 1.0
	v_pk_mul_f32 v[76:77], v[76:77], v[84:85] op_sel_hi:[1,0]
	v_pk_mul_f32 v[78:79], v[78:79], v[84:85] op_sel_hi:[1,0]
	v_pk_mul_f32 v[72:73], v[72:73], v[84:85] op_sel_hi:[1,0]
	v_pk_mul_f32 v[74:75], v[74:75], v[84:85] op_sel_hi:[1,0]
	v_pk_mul_f32 v[86:87], v[68:69], v[84:85] op_sel_hi:[1,0]
	v_pk_mul_f32 v[88:89], v[70:71], v[84:85] op_sel_hi:[1,0]
	v_pk_mul_f32 v[90:91], v[64:65], v[84:85] op_sel_hi:[1,0]
	v_pk_mul_f32 v[84:85], v[66:67], v[84:85] op_sel_hi:[1,0]
	v_pk_mul_f32 v[214:215], v[142:143], v[78:79]
	v_pk_mul_f32 v[212:213], v[140:141], v[76:77]
	v_pk_mul_f32 v[218:219], v[138:139], v[74:75]
	v_pk_mul_f32 v[216:217], v[136:137], v[72:73]
	v_pk_mul_f32 v[222:223], v[134:135], v[88:89]
	v_pk_mul_f32 v[220:221], v[132:133], v[86:87]
	v_pk_mul_f32 v[226:227], v[130:131], v[84:85]
	v_pk_mul_f32 v[224:225], v[128:129], v[90:91]
	s_waitcnt vmcnt(12)
;     __device__ __forceinline__ void after(f32x4 (&acc)[2][2][4][2], const Unit& u, int wr, int wc, int fr, int fq) const {
;     ...
; #pragma unroll
;         for (int ai = 0; ai < 2; ++ai)
; #pragma unroll
;             for (int m = 0; m < 4; ++m) {
;                 const int row = 256 * u.pm + 128 * ai + 64 * wr + 16 * m + fr;
;                 const f32x4* sp = (const f32x4*)(SSQ + row * 16);
;                 const f32x4 s0 = sp[0], s1 = sp[1], s2 = sp[2], s3 = sp[3];
;                 const float tot = ((s0[0] + s0[1]) + (s0[2] + s0[3])) + ((s1[0] + s1[1]) + (s1[2] + s1[3])) + ((s2[0] + s2[1]) + (s2[2] + s2[3])) + ((s3[0] + s3[1]) + (s3[2] + s3[3]));
;                 const float rinv = 1.0f / sqrtf(tot * (1.f / DM) + 1e-6f);
; #pragma unroll
;                 for (int bj = 0; bj < 2; ++bj)
; #pragma unroll
;                     for (int n = 0; n < 2; ++n) {
;                         const int col = 256 * u.pn + 64 * wc + 32 * bj + 8 * fq + 4 * n;
;                         *(f32x4*)(out + (size_t)row * 1024 + col) = acc[ai][bj][m][n] * rinv * gn[bj][n];
;                     }
;             }
	v_mov_b32_e32 v64, v176
	v_mov_b32_e32 v65, v177
	v_mov_b32_e32 v66, v178
	v_mov_b32_e32 v67, v179
	v_mov_b32_e32 v68, v180
	v_mov_b32_e32 v69, v181
	v_mov_b32_e32 v70, v182
	v_mov_b32_e32 v71, v183
	v_mov_b32_e32 v72, v184
	v_mov_b32_e32 v73, v185
	v_mov_b32_e32 v74, v186
	v_mov_b32_e32 v75, v187
	v_mov_b32_e32 v76, v188
	v_mov_b32_e32 v77, v189
	v_mov_b32_e32 v78, v190
	v_mov_b32_e32 v79, v191
	global_load_dwordx4 v[176:179], v[246:247], off offset:2048
	global_load_dwordx4 v[180:183], v[246:247], off offset:2064
	global_load_dwordx4 v[184:187], v[246:247], off offset:2080
	global_load_dwordx4 v[188:191], v[246:247], off offset:2096
	global_store_dwordx4 v[80:81], v[212:215], off
	global_store_dwordx4 v[80:81], v[216:219], off offset:16
	global_store_dwordx4 v[80:81], v[220:223], off offset:128
	global_store_dwordx4 v[80:81], v[224:227], off offset:144
	v_add_u32_e32 v80, 0x90, v146
	v_lshlrev_b64 v[84:85], 12, v[96:97]
	v_lshlrev_b32_e32 v82, 4, v80
	v_ashrrev_i32_e32 v83, 31, v82
	v_ashrrev_i32_e32 v81, 31, v80
	v_mov_b32_e32 v86, v65
	v_mov_b32_e32 v87, v66
	v_mov_b32_e32 v65, v67
	v_mov_b32_e32 v66, v69
	v_mov_b32_e32 v67, v70
	v_mov_b32_e32 v69, v71
	v_pk_add_f32 v[64:65], v[86:87], v[64:65]
	v_pk_add_f32 v[66:67], v[66:67], v[68:69]
	v_pk_add_f32 v[64:65], v[64:65], v[64:65] op_sel:[0,1] op_sel_hi:[1,0]
	v_pk_add_f32 v[66:67], v[66:67], v[66:67] op_sel:[0,1] op_sel_hi:[1,0]
	v_add_f32_e32 v70, v72, v73
	v_add_f32_e32 v72, v74, v75
	v_mov_b32_e32 v71, v78
	v_mov_b32_e32 v73, v79
	v_mov_b32_e32 v65, v76
	v_mov_b32_e32 v67, v77
	v_pk_add_f32 v[68:69], v[70:71], v[72:73]
	v_pk_add_f32 v[64:65], v[64:65], v[66:67]
	v_lshl_add_u64 v[66:67], v[82:83], 2, s[6:7]
	v_pk_add_f32 v[64:65], v[64:65], v[68:69]
	s_nop 0
	v_add_f32_e32 v64, v64, v65
	v_fmamk_f32 v64, v64, 0x3a800000, v149
	v_mul_f32_e32 v65, 0x4f800000, v64
	v_cmp_gt_f32_e32 vcc, s2, v64
	s_nop 1
	v_cndmask_b32_e32 v68, v64, v65, vcc
	v_sqrt_f32_e32 v69, v68
	v_lshl_add_u64 v[64:65], s[74:75], 0, v[84:85]
	v_lshl_add_u64 v[64:65], v[64:65], 0, v[144:145]
	v_add_u32_e32 v70, -1, v69
	v_add_u32_e32 v71, 1, v69
	v_fma_f32 v72, -v70, v69, v68
	v_fma_f32 v73, -v71, v69, v68
	v_cmp_ge_f32_e64 s[0:1], 0, v72
	s_nop 1
	v_cndmask_b32_e64 v69, v69, v70, s[0:1]
	v_cmp_lt_f32_e64 s[0:1], 0, v73
	s_nop 1
	v_cndmask_b32_e64 v69, v69, v71, s[0:1]
	v_mul_f32_e32 v70, 0x37800000, v69
	v_cndmask_b32_e32 v69, v69, v70, vcc
	v_cmp_class_f32_e32 vcc, v68, v148
	s_nop 1
	v_cndmask_b32_e32 v68, v69, v68, vcc
	v_div_scale_f32 v69, s[0:1], v68, v68, 1.0
	v_rcp_f32_e32 v70, v69
	v_div_scale_f32 v71, vcc, 1.0, v68, 1.0
	v_fma_f32 v72, -v69, v70, 1.0
	v_fmac_f32_e32 v70, v72, v70
	v_mul_f32_e32 v72, v71, v70
	v_fma_f32 v73, -v69, v72, v71
	v_fmac_f32_e32 v72, v73, v70
	v_fma_f32 v69, -v69, v72, v71
	v_div_fmas_f32 v69, v69, v70, v72
	v_div_fixup_f32 v68, v69, v68, 1.0
	v_pk_mul_f32 v[60:61], v[60:61], v[68:69] op_sel_hi:[1,0]
	v_pk_mul_f32 v[62:63], v[62:63], v[68:69] op_sel_hi:[1,0]
	v_pk_mul_f32 v[56:57], v[56:57], v[68:69] op_sel_hi:[1,0]
	v_pk_mul_f32 v[58:59], v[58:59], v[68:69] op_sel_hi:[1,0]
	v_pk_mul_f32 v[70:71], v[52:53], v[68:69] op_sel_hi:[1,0]
	v_pk_mul_f32 v[72:73], v[54:55], v[68:69] op_sel_hi:[1,0]
	v_pk_mul_f32 v[74:75], v[48:49], v[68:69] op_sel_hi:[1,0]
	v_pk_mul_f32 v[68:69], v[50:51], v[68:69] op_sel_hi:[1,0]
	v_pk_mul_f32 v[198:199], v[142:143], v[62:63]
	v_pk_mul_f32 v[196:197], v[140:141], v[60:61]
	v_pk_mul_f32 v[202:203], v[138:139], v[58:59]
	v_pk_mul_f32 v[200:201], v[136:137], v[56:57]
	v_pk_mul_f32 v[206:207], v[134:135], v[72:73]
	v_pk_mul_f32 v[204:205], v[132:133], v[70:71]
	v_pk_mul_f32 v[210:211], v[130:131], v[68:69]
	v_pk_mul_f32 v[208:209], v[128:129], v[74:75]
	s_waitcnt vmcnt(12)
	v_mov_b32_e32 v48, v228
	v_mov_b32_e32 v49, v229
	v_mov_b32_e32 v50, v230
	v_mov_b32_e32 v51, v231
	v_mov_b32_e32 v52, v232
	v_mov_b32_e32 v53, v233
	v_mov_b32_e32 v54, v234
	v_mov_b32_e32 v55, v235
	v_mov_b32_e32 v56, v236
	v_mov_b32_e32 v57, v237
	v_mov_b32_e32 v58, v238
	v_mov_b32_e32 v59, v239
	v_mov_b32_e32 v60, v240
	v_mov_b32_e32 v61, v241
	v_mov_b32_e32 v62, v242
	v_mov_b32_e32 v63, v243
	global_load_dwordx4 v[228:231], v[246:247], off offset:3072
	global_load_dwordx4 v[232:235], v[246:247], off offset:3088
	global_load_dwordx4 v[236:239], v[246:247], off offset:3104
	global_load_dwordx4 v[240:243], v[246:247], off offset:3120
	global_store_dwordx4 v[64:65], v[196:199], off
	global_store_dwordx4 v[64:65], v[200:203], off offset:16
	global_store_dwordx4 v[64:65], v[204:207], off offset:128
	global_store_dwordx4 v[64:65], v[208:211], off offset:144
	v_add_u32_e32 v64, 0xa0, v146
	v_lshlrev_b64 v[68:69], 12, v[80:81]
	v_lshlrev_b32_e32 v66, 4, v64
	v_ashrrev_i32_e32 v67, 31, v66
	v_ashrrev_i32_e32 v65, 31, v64
	v_mov_b32_e32 v70, v49
	v_mov_b32_e32 v71, v50
	v_mov_b32_e32 v49, v51
	v_mov_b32_e32 v50, v53
	v_mov_b32_e32 v51, v54
	v_mov_b32_e32 v53, v55
	v_pk_add_f32 v[48:49], v[70:71], v[48:49]
	v_pk_add_f32 v[50:51], v[50:51], v[52:53]
	v_pk_add_f32 v[48:49], v[48:49], v[48:49] op_sel:[0,1] op_sel_hi:[1,0]
	v_pk_add_f32 v[50:51], v[50:51], v[50:51] op_sel:[0,1] op_sel_hi:[1,0]
	v_add_f32_e32 v54, v56, v57
	v_add_f32_e32 v56, v58, v59
	v_mov_b32_e32 v55, v62
	v_mov_b32_e32 v57, v63
	v_mov_b32_e32 v49, v60
	v_mov_b32_e32 v51, v61
	v_pk_add_f32 v[52:53], v[54:55], v[56:57]
	v_pk_add_f32 v[48:49], v[48:49], v[50:51]
	v_lshl_add_u64 v[50:51], v[66:67], 2, s[6:7]
	v_pk_add_f32 v[48:49], v[48:49], v[52:53]
	s_nop 0
	v_add_f32_e32 v48, v48, v49
	v_fmamk_f32 v48, v48, 0x3a800000, v149
	v_mul_f32_e32 v49, 0x4f800000, v48
	v_cmp_gt_f32_e32 vcc, s2, v48
	s_nop 1
	v_cndmask_b32_e32 v52, v48, v49, vcc
;     __device__ __forceinline__ void after(f32x4 (&acc)[2][2][4][2], const Unit& u, int wr, int wc, int fr, int fq) const {
;     ...
; #pragma unroll
;         for (int ai = 0; ai < 2; ++ai)
; #pragma unroll
;             for (int m = 0; m < 4; ++m) {
;                 const int row = 256 * u.pm + 128 * ai + 64 * wr + 16 * m + fr;
;                 const f32x4* sp = (const f32x4*)(SSQ + row * 16);
;                 const f32x4 s0 = sp[0], s1 = sp[1], s2 = sp[2], s3 = sp[3];
;                 const float tot = ((s0[0] + s0[1]) + (s0[2] + s0[3])) + ((s1[0] + s1[1]) + (s1[2] + s1[3])) + ((s2[0] + s2[1]) + (s2[2] + s2[3])) + ((s3[0] + s3[1]) + (s3[2] + s3[3]));
;                 const float rinv = 1.0f / sqrtf(tot * (1.f / DM) + 1e-6f);
; #pragma unroll
;                 for (int bj = 0; bj < 2; ++bj)
; #pragma unroll
;                     for (int n = 0; n < 2; ++n) {
;                         const int col = 256 * u.pn + 64 * wc + 32 * bj + 8 * fq + 4 * n;
;                         *(f32x4*)(out + (size_t)row * 1024 + col) = acc[ai][bj][m][n] * rinv * gn[bj][n];
;                     }
;             }
	v_sqrt_f32_e32 v53, v52
	v_lshl_add_u64 v[48:49], s[74:75], 0, v[68:69]
	v_lshl_add_u64 v[48:49], v[48:49], 0, v[144:145]
	v_add_u32_e32 v54, -1, v53
	v_add_u32_e32 v55, 1, v53
	v_fma_f32 v56, -v54, v53, v52
	v_fma_f32 v57, -v55, v53, v52
	v_cmp_ge_f32_e64 s[0:1], 0, v56
	s_nop 1
	v_cndmask_b32_e64 v53, v53, v54, s[0:1]
	v_cmp_lt_f32_e64 s[0:1], 0, v57
	s_nop 1
	v_cndmask_b32_e64 v53, v53, v55, s[0:1]
	v_mul_f32_e32 v54, 0x37800000, v53
	v_cndmask_b32_e32 v53, v53, v54, vcc
	v_cmp_class_f32_e32 vcc, v52, v148
	s_nop 1
	v_cndmask_b32_e32 v52, v53, v52, vcc
	v_div_scale_f32 v53, s[0:1], v52, v52, 1.0
	v_rcp_f32_e32 v54, v53
	v_div_scale_f32 v55, vcc, 1.0, v52, 1.0
	v_fma_f32 v56, -v53, v54, 1.0
	v_fmac_f32_e32 v54, v56, v54
	v_mul_f32_e32 v56, v55, v54
	v_fma_f32 v57, -v53, v56, v55
	v_fmac_f32_e32 v56, v57, v54
	v_fma_f32 v53, -v53, v56, v55
	v_div_fmas_f32 v53, v53, v54, v56
	v_div_fixup_f32 v52, v53, v52, 1.0
	v_pk_mul_f32 v[44:45], v[44:45], v[52:53] op_sel_hi:[1,0]
	v_pk_mul_f32 v[46:47], v[46:47], v[52:53] op_sel_hi:[1,0]
	v_pk_mul_f32 v[40:41], v[40:41], v[52:53] op_sel_hi:[1,0]
	v_pk_mul_f32 v[42:43], v[42:43], v[52:53] op_sel_hi:[1,0]
	v_pk_mul_f32 v[54:55], v[36:37], v[52:53] op_sel_hi:[1,0]
	v_pk_mul_f32 v[56:57], v[38:39], v[52:53] op_sel_hi:[1,0]
	v_pk_mul_f32 v[58:59], v[32:33], v[52:53] op_sel_hi:[1,0]
	v_pk_mul_f32 v[52:53], v[34:35], v[52:53] op_sel_hi:[1,0]
	v_pk_mul_f32 v[214:215], v[142:143], v[46:47]
	v_pk_mul_f32 v[212:213], v[140:141], v[44:45]
	v_pk_mul_f32 v[218:219], v[138:139], v[42:43]
	v_pk_mul_f32 v[216:217], v[136:137], v[40:41]
	v_pk_mul_f32 v[222:223], v[134:135], v[56:57]
	v_pk_mul_f32 v[220:221], v[132:133], v[54:55]
	v_pk_mul_f32 v[226:227], v[130:131], v[52:53]
	v_pk_mul_f32 v[224:225], v[128:129], v[58:59]
	s_waitcnt vmcnt(12)
	v_mov_b32_e32 v32, v176
	v_mov_b32_e32 v33, v177
	v_mov_b32_e32 v34, v178
	v_mov_b32_e32 v35, v179
	v_mov_b32_e32 v36, v180
	v_mov_b32_e32 v37, v181
	v_mov_b32_e32 v38, v182
	v_mov_b32_e32 v39, v183
	v_mov_b32_e32 v40, v184
	v_mov_b32_e32 v41, v185
	v_mov_b32_e32 v42, v186
	v_mov_b32_e32 v43, v187
	v_mov_b32_e32 v44, v188
	v_mov_b32_e32 v45, v189
	v_mov_b32_e32 v46, v190
	v_mov_b32_e32 v47, v191
	global_store_dwordx4 v[48:49], v[212:215], off
	global_store_dwordx4 v[48:49], v[216:219], off offset:16
	global_store_dwordx4 v[48:49], v[220:223], off offset:128
	global_store_dwordx4 v[48:49], v[224:227], off offset:144
	v_add_u32_e32 v48, 0xb0, v146
	v_lshlrev_b64 v[52:53], 12, v[64:65]
	v_lshlrev_b32_e32 v50, 4, v48
	v_ashrrev_i32_e32 v51, 31, v50
	v_ashrrev_i32_e32 v49, 31, v48
	v_mov_b32_e32 v54, v33
	v_mov_b32_e32 v55, v34
	v_mov_b32_e32 v33, v35
	v_mov_b32_e32 v34, v37
	v_mov_b32_e32 v35, v38
	v_mov_b32_e32 v37, v39
	v_pk_add_f32 v[32:33], v[54:55], v[32:33]
	v_pk_add_f32 v[34:35], v[34:35], v[36:37]
	v_pk_add_f32 v[32:33], v[32:33], v[32:33] op_sel:[0,1] op_sel_hi:[1,0]
	v_pk_add_f32 v[34:35], v[34:35], v[34:35] op_sel:[0,1] op_sel_hi:[1,0]
	v_add_f32_e32 v38, v40, v41
	v_add_f32_e32 v40, v42, v43
	v_mov_b32_e32 v39, v46
	v_mov_b32_e32 v41, v47
	v_mov_b32_e32 v33, v44
	v_mov_b32_e32 v35, v45
	v_pk_add_f32 v[36:37], v[38:39], v[40:41]
	v_pk_add_f32 v[32:33], v[32:33], v[34:35]
	v_lshl_add_u64 v[34:35], v[50:51], 2, s[6:7]
	v_pk_add_f32 v[32:33], v[32:33], v[36:37]
	s_nop 0
	v_add_f32_e32 v32, v32, v33
	v_fmamk_f32 v32, v32, 0x3a800000, v149
	v_mul_f32_e32 v33, 0x4f800000, v32
	v_cmp_gt_f32_e32 vcc, s2, v32
	s_nop 1
	v_cndmask_b32_e32 v36, v32, v33, vcc
	v_sqrt_f32_e32 v37, v36
	v_lshl_add_u64 v[32:33], s[74:75], 0, v[52:53]
	v_lshl_add_u64 v[32:33], v[32:33], 0, v[144:145]
	v_add_u32_e32 v38, -1, v37
	v_add_u32_e32 v39, 1, v37
	v_fma_f32 v40, -v38, v37, v36
	v_fma_f32 v41, -v39, v37, v36
	v_cmp_ge_f32_e64 s[0:1], 0, v40
	s_nop 1
	v_cndmask_b32_e64 v37, v37, v38, s[0:1]
	v_cmp_lt_f32_e64 s[0:1], 0, v41
	s_nop 1
	v_cndmask_b32_e64 v37, v37, v39, s[0:1]
	v_mul_f32_e32 v38, 0x37800000, v37
	v_cndmask_b32_e32 v37, v37, v38, vcc
	v_cmp_class_f32_e32 vcc, v36, v148
	s_nop 1
	v_cndmask_b32_e32 v36, v37, v36, vcc
	v_div_scale_f32 v37, s[0:1], v36, v36, 1.0
	v_rcp_f32_e32 v38, v37
	v_div_scale_f32 v39, vcc, 1.0, v36, 1.0
	v_fma_f32 v40, -v37, v38, 1.0
	v_fmac_f32_e32 v38, v40, v38
	v_mul_f32_e32 v40, v39, v38
	v_fma_f32 v41, -v37, v40, v39
	v_fmac_f32_e32 v40, v41, v38
	v_fma_f32 v37, -v37, v40, v39
	v_div_fmas_f32 v37, v37, v38, v40
	v_div_fixup_f32 v36, v37, v36, 1.0
	v_pk_mul_f32 v[28:29], v[28:29], v[36:37] op_sel_hi:[1,0]
	v_pk_mul_f32 v[30:31], v[30:31], v[36:37] op_sel_hi:[1,0]
	v_pk_mul_f32 v[24:25], v[24:25], v[36:37] op_sel_hi:[1,0]
	v_pk_mul_f32 v[26:27], v[26:27], v[36:37] op_sel_hi:[1,0]
	v_pk_mul_f32 v[38:39], v[20:21], v[36:37] op_sel_hi:[1,0]
	v_pk_mul_f32 v[40:41], v[22:23], v[36:37] op_sel_hi:[1,0]
	v_pk_mul_f32 v[42:43], v[16:17], v[36:37] op_sel_hi:[1,0]
	v_pk_mul_f32 v[36:37], v[18:19], v[36:37] op_sel_hi:[1,0]
	v_pk_mul_f32 v[198:199], v[142:143], v[30:31]
	v_pk_mul_f32 v[196:197], v[140:141], v[28:29]
	v_pk_mul_f32 v[202:203], v[138:139], v[26:27]
	v_pk_mul_f32 v[200:201], v[136:137], v[24:25]
	v_pk_mul_f32 v[206:207], v[134:135], v[40:41]
	v_pk_mul_f32 v[204:205], v[132:133], v[38:39]
	v_pk_mul_f32 v[210:211], v[130:131], v[36:37]
	v_pk_mul_f32 v[208:209], v[128:129], v[42:43]
	s_waitcnt vmcnt(8)
;     __device__ __forceinline__ void after(f32x4 (&acc)[2][2][4][2], const Unit& u, int wr, int wc, int fr, int fq) const {
;     ...
; #pragma unroll
;         for (int ai = 0; ai < 2; ++ai)
; #pragma unroll
;             for (int m = 0; m < 4; ++m) {
;                 const int row = 256 * u.pm + 128 * ai + 64 * wr + 16 * m + fr;
;                 const f32x4* sp = (const f32x4*)(SSQ + row * 16);
;                 const f32x4 s0 = sp[0], s1 = sp[1], s2 = sp[2], s3 = sp[3];
;                 const float tot = ((s0[0] + s0[1]) + (s0[2] + s0[3])) + ((s1[0] + s1[1]) + (s1[2] + s1[3])) + ((s2[0] + s2[1]) + (s2[2] + s2[3])) + ((s3[0] + s3[1]) + (s3[2] + s3[3]));
;                 const float rinv = 1.0f / sqrtf(tot * (1.f / DM) + 1e-6f);
; #pragma unroll
;                 for (int bj = 0; bj < 2; ++bj)
; #pragma unroll
;                     for (int n = 0; n < 2; ++n) {
;                         const int col = 256 * u.pn + 64 * wc + 32 * bj + 8 * fq + 4 * n;
;                         *(f32x4*)(out + (size_t)row * 1024 + col) = acc[ai][bj][m][n] * rinv * gn[bj][n];
;                     }
;             }
	v_mov_b32_e32 v16, v228
	v_mov_b32_e32 v17, v229
	v_mov_b32_e32 v18, v230
	v_mov_b32_e32 v19, v231
	v_mov_b32_e32 v20, v232
	v_mov_b32_e32 v21, v233
	v_mov_b32_e32 v22, v234
	v_mov_b32_e32 v23, v235
	v_mov_b32_e32 v24, v236
	v_mov_b32_e32 v25, v237
	v_mov_b32_e32 v26, v238
	v_mov_b32_e32 v27, v239
	v_mov_b32_e32 v28, v240
	v_mov_b32_e32 v29, v241
	v_mov_b32_e32 v30, v242
	v_mov_b32_e32 v31, v243
	global_store_dwordx4 v[32:33], v[196:199], off
	global_store_dwordx4 v[32:33], v[200:203], off offset:16
	global_store_dwordx4 v[32:33], v[204:207], off offset:128
	global_store_dwordx4 v[32:33], v[208:211], off offset:144
	v_mov_b32_e32 v32, v17
	v_mov_b32_e32 v33, v18
	v_mov_b32_e32 v17, v19
	v_mov_b32_e32 v18, v21
	v_mov_b32_e32 v19, v22
	v_mov_b32_e32 v21, v23
	v_pk_add_f32 v[16:17], v[32:33], v[16:17]
	v_pk_add_f32 v[18:19], v[18:19], v[20:21]
	v_pk_add_f32 v[16:17], v[16:17], v[16:17] op_sel:[0,1] op_sel_hi:[1,0]
	v_pk_add_f32 v[18:19], v[18:19], v[18:19] op_sel:[0,1] op_sel_hi:[1,0]
	v_add_f32_e32 v22, v24, v25
	v_add_f32_e32 v24, v26, v27
	v_mov_b32_e32 v23, v30
	v_mov_b32_e32 v25, v31
	v_mov_b32_e32 v17, v28
	v_mov_b32_e32 v19, v29
	v_pk_add_f32 v[20:21], v[22:23], v[24:25]
	v_pk_add_f32 v[16:17], v[16:17], v[18:19]
	s_nop 0
	v_pk_add_f32 v[16:17], v[16:17], v[20:21]
	s_nop 0
	v_add_f32_e32 v16, v16, v17
	v_fmac_f32_e32 v149, 0x3a800000, v16
	v_mul_f32_e32 v16, 0x4f800000, v149
	v_cmp_gt_f32_e32 vcc, s2, v149
	s_nop 1
	v_cndmask_b32_e32 v18, v149, v16, vcc
	v_sqrt_f32_e32 v19, v18
	v_lshlrev_b64 v[16:17], 12, v[48:49]
	v_lshl_add_u64 v[16:17], s[74:75], 0, v[16:17]
	v_lshl_add_u64 v[16:17], v[16:17], 0, v[144:145]
	v_add_u32_e32 v20, -1, v19
	v_add_u32_e32 v21, 1, v19
	v_fma_f32 v22, -v20, v19, v18
	v_fma_f32 v23, -v21, v19, v18
	v_cmp_ge_f32_e64 s[0:1], 0, v22
	s_nop 1
	v_cndmask_b32_e64 v19, v19, v20, s[0:1]
	v_cmp_lt_f32_e64 s[0:1], 0, v23
	s_nop 1
	v_cndmask_b32_e64 v19, v19, v21, s[0:1]
	v_mul_f32_e32 v20, 0x37800000, v19
	v_cndmask_b32_e32 v19, v19, v20, vcc
	v_cmp_class_f32_e32 vcc, v18, v148
	s_nop 1
	v_cndmask_b32_e32 v18, v19, v18, vcc
	v_div_scale_f32 v19, s[0:1], v18, v18, 1.0
	v_rcp_f32_e32 v20, v19
	v_div_scale_f32 v21, vcc, 1.0, v18, 1.0
	v_fma_f32 v22, -v19, v20, 1.0
	v_fmac_f32_e32 v20, v22, v20
	v_mul_f32_e32 v22, v21, v20
	v_fma_f32 v23, -v19, v22, v21
	v_fmac_f32_e32 v22, v23, v20
	v_fma_f32 v19, -v19, v22, v21
	v_div_fmas_f32 v19, v19, v20, v22
	v_div_fixup_f32 v18, v19, v18, 1.0
	v_pk_mul_f32 v[12:13], v[12:13], v[18:19] op_sel_hi:[1,0]
	v_pk_mul_f32 v[14:15], v[14:15], v[18:19] op_sel_hi:[1,0]
	v_pk_mul_f32 v[8:9], v[8:9], v[18:19] op_sel_hi:[1,0]
	v_pk_mul_f32 v[10:11], v[10:11], v[18:19] op_sel_hi:[1,0]
	v_pk_mul_f32 v[20:21], v[4:5], v[18:19] op_sel_hi:[1,0]
	v_pk_mul_f32 v[22:23], v[6:7], v[18:19] op_sel_hi:[1,0]
	v_pk_mul_f32 v[24:25], v[0:1], v[18:19] op_sel_hi:[1,0]
	v_pk_mul_f32 v[18:19], v[2:3], v[18:19] op_sel_hi:[1,0]
	v_pk_mul_f32 v[2:3], v[142:143], v[14:15]
	v_pk_mul_f32 v[0:1], v[140:141], v[12:13]
	v_pk_mul_f32 v[6:7], v[138:139], v[10:11]
	v_pk_mul_f32 v[4:5], v[136:137], v[8:9]
	v_pk_mul_f32 v[10:11], v[134:135], v[22:23]
	v_pk_mul_f32 v[8:9], v[132:133], v[20:21]
	v_pk_mul_f32 v[14:15], v[130:131], v[18:19]
	v_pk_mul_f32 v[12:13], v[128:129], v[24:25]
	global_store_dwordx4 v[16:17], v[0:3], off
	global_store_dwordx4 v[16:17], v[4:7], off offset:16
	global_store_dwordx4 v[16:17], v[8:11], off offset:128
	global_store_dwordx4 v[16:17], v[12:15], off offset:144
	s_endpgm
